# v_combo14 + GEMM (P0/P5/P8) row-scale loads issued in the last K-loop trip (third load segment, counted wait adjusted in that trip), epilogue vmcnt(0) dropped
# baseline (speedup 1.0000x reference)
.LBB0_236:
	ds_read_b128 v[154:157], v150
	ds_read_b128 v[158:161], v150 offset:1024
	ds_read_b128 v[162:165], v150 offset:2048
	ds_read_b128 v[166:169], v150 offset:3072
	ds_read_b128 v[172:175], v151
	ds_read_b128 v[176:179], v151 offset:1024
	ds_read_b128 v[180:183], v151 offset:2048
	ds_read_b128 v[184:187], v151 offset:3072
	s_add_u32 s36, s34, 0xfffc0080
	s_addc_u32 s37, s35, -1
	s_cmp_eq_u32 s66, 12
	s_cselect_b32 s39, s21, s37
	s_cselect_b32 s38, s62, s36
	s_cselect_b32 s37, s19, s65
	s_cselect_b32 s36, s63, s64
	v_lshl_add_u64 v[220:221], s[34:35], 0, v[138:139]
	s_add_i32 m0, s27, 0xc000
	ds_read_b128 v[188:191], v152
	ds_read_b128 v[192:195], v152 offset:1024
	ds_read_b128 v[196:199], v152 offset:2048
	ds_read_b128 v[200:203], v152 offset:3072
	ds_read_b128 v[204:207], v152 offset:4096
	ds_read_b128 v[208:211], v152 offset:5120
	ds_read_b128 v[212:215], v152 offset:6144
	ds_read_b128 v[216:219], v152 offset:7168
	global_load_lds_dwordx4 v[220:221], off
	v_lshl_add_u64 v[220:221], s[34:35], 0, v[140:141]
	s_add_i32 m0, s27, 0xe000
	s_nop 0
	global_load_lds_dwordx4 v[220:221], off
	s_waitcnt vmcnt(8)
	s_waitcnt lgkmcnt(0)
	s_barrier
	s_setprio 1
	s_waitcnt lgkmcnt(0)
	v_mfma_f32_16x16x32_bf16 v[124:127], v[154:157], v[188:191], v[124:127]
	v_mfma_f32_16x16x32_bf16 v[120:123], v[162:165], v[188:191], v[120:123]
	v_mfma_f32_16x16x32_bf16 v[116:119], v[154:157], v[196:199], v[116:119]
	v_mfma_f32_16x16x32_bf16 v[112:115], v[162:165], v[196:199], v[112:115]
	v_mfma_f32_16x16x32_bf16 v[108:111], v[154:157], v[204:207], v[108:111]
	v_mfma_f32_16x16x32_bf16 v[100:103], v[162:165], v[204:207], v[100:103]
	v_mfma_f32_16x16x32_bf16 v[76:79], v[154:157], v[212:215], v[76:79]
	v_mfma_f32_16x16x32_bf16 v[72:75], v[162:165], v[212:215], v[72:75]
	v_mfma_f32_16x16x32_bf16 v[124:127], v[158:161], v[192:195], v[124:127]
	v_mfma_f32_16x16x32_bf16 v[120:123], v[166:169], v[192:195], v[120:123]
	v_mfma_f32_16x16x32_bf16 v[116:119], v[158:161], v[200:203], v[116:119]
	v_mfma_f32_16x16x32_bf16 v[112:115], v[166:169], v[200:203], v[112:115]
	v_mfma_f32_16x16x32_bf16 v[108:111], v[158:161], v[208:211], v[108:111]
	v_mfma_f32_16x16x32_bf16 v[100:103], v[166:169], v[208:211], v[100:103]
	v_mfma_f32_16x16x32_bf16 v[76:79], v[158:161], v[216:219], v[76:79]
	v_mfma_f32_16x16x32_bf16 v[72:75], v[166:169], v[216:219], v[72:75]
	s_setprio 0
	s_setprio 1
	v_mfma_f32_16x16x32_bf16 v[104:107], v[172:175], v[188:191], v[104:107]
	v_mfma_f32_16x16x32_bf16 v[96:99], v[180:183], v[188:191], v[96:99]
	v_mfma_f32_16x16x32_bf16 v[92:95], v[172:175], v[196:199], v[92:95]
	v_mfma_f32_16x16x32_bf16 v[88:91], v[180:183], v[196:199], v[88:91]
	v_mfma_f32_16x16x32_bf16 v[84:87], v[172:175], v[204:207], v[84:87]
	v_mfma_f32_16x16x32_bf16 v[80:83], v[180:183], v[204:207], v[80:83]
	v_mfma_f32_16x16x32_bf16 v[68:71], v[172:175], v[212:215], v[68:71]
	v_mfma_f32_16x16x32_bf16 v[64:67], v[180:183], v[212:215], v[64:67]
	v_mfma_f32_16x16x32_bf16 v[104:107], v[176:179], v[192:195], v[104:107]
	v_mfma_f32_16x16x32_bf16 v[96:99], v[184:187], v[192:195], v[96:99]
	v_mfma_f32_16x16x32_bf16 v[92:95], v[176:179], v[200:203], v[92:95]
	v_mfma_f32_16x16x32_bf16 v[88:91], v[184:187], v[200:203], v[88:91]
	v_mfma_f32_16x16x32_bf16 v[84:87], v[176:179], v[208:211], v[84:87]
	v_mfma_f32_16x16x32_bf16 v[80:83], v[184:187], v[208:211], v[80:83]
	v_mfma_f32_16x16x32_bf16 v[68:71], v[176:179], v[216:219], v[68:71]
	v_mfma_f32_16x16x32_bf16 v[64:67], v[184:187], v[216:219], v[64:67]
	s_setprio 0
	s_barrier
	s_add_i32 s67, s54, s43
	v_lshl_add_u64 v[220:221], s[36:37], 0, v[132:133]
	s_mov_b32 m0, s67
	ds_read_b128 v[188:191], v152 offset:16384
	ds_read_b128 v[192:195], v152 offset:17408
	ds_read_b128 v[196:199], v152 offset:18432
	ds_read_b128 v[200:203], v152 offset:19456
	ds_read_b128 v[204:207], v152 offset:20480
	ds_read_b128 v[208:211], v152 offset:21504
	ds_read_b128 v[212:215], v152 offset:22528
	ds_read_b128 v[216:219], v152 offset:23552
	global_load_lds_dwordx4 v[220:221], off
	s_add_i32 m0, s67, 0x2000
	s_add_u32 s68, s36, 0x40000
	v_lshl_add_u64 v[222:223], s[36:37], 0, v[128:129]
	s_addc_u32 s69, s37, 0
	s_add_i32 s67, s55, s43
	global_load_lds_dwordx4 v[222:223], off
	v_lshl_add_u64 v[224:225], s[68:69], 0, v[132:133]
	s_mov_b32 m0, s67
	v_lshl_add_u64 v[226:227], s[38:39], 0, v[130:131]
	global_load_lds_dwordx4 v[224:225], off
	v_lshl_add_u64 v[224:225], s[68:69], 0, v[128:129]
	s_add_i32 m0, s67, 0x2000
	s_nop 0
	global_load_lds_dwordx4 v[224:225], off
	v_lshl_add_u64 v[224:225], s[38:39], 0, v[134:135]
	s_mov_b32 m0, s27
	s_nop 0
	global_load_lds_dwordx4 v[224:225], off
	s_mov_b32 m0, s46
	s_nop 0
	global_load_lds_dwordx4 v[226:227], off
	s_waitcnt vmcnt(8)
	s_waitcnt lgkmcnt(0)
	s_barrier
	s_setprio 1
	s_waitcnt lgkmcnt(0)
	v_mfma_f32_16x16x32_bf16 v[60:63], v[154:157], v[188:191], v[60:63]
	v_mfma_f32_16x16x32_bf16 v[56:59], v[162:165], v[188:191], v[56:59]
	v_mfma_f32_16x16x32_bf16 v[52:55], v[154:157], v[196:199], v[52:55]
	v_mfma_f32_16x16x32_bf16 v[44:47], v[162:165], v[196:199], v[44:47]
	v_mfma_f32_16x16x32_bf16 v[36:39], v[154:157], v[204:207], v[36:39]
	v_mfma_f32_16x16x32_bf16 v[28:31], v[162:165], v[204:207], v[28:31]
	v_mfma_f32_16x16x32_bf16 v[20:23], v[154:157], v[212:215], v[20:23]
	v_mfma_f32_16x16x32_bf16 v[12:15], v[162:165], v[212:215], v[12:15]
	v_mfma_f32_16x16x32_bf16 v[60:63], v[158:161], v[192:195], v[60:63]
	v_mfma_f32_16x16x32_bf16 v[56:59], v[166:169], v[192:195], v[56:59]
	v_mfma_f32_16x16x32_bf16 v[52:55], v[158:161], v[200:203], v[52:55]
	v_mfma_f32_16x16x32_bf16 v[44:47], v[166:169], v[200:203], v[44:47]
	v_mfma_f32_16x16x32_bf16 v[36:39], v[158:161], v[208:211], v[36:39]
	v_mfma_f32_16x16x32_bf16 v[28:31], v[166:169], v[208:211], v[28:31]
	v_mfma_f32_16x16x32_bf16 v[20:23], v[158:161], v[216:219], v[20:23]
	v_mfma_f32_16x16x32_bf16 v[12:15], v[166:169], v[216:219], v[12:15]
	s_setprio 0
	s_setprio 1
	v_mfma_f32_16x16x32_bf16 v[48:51], v[172:175], v[188:191], v[48:51]
	v_mfma_f32_16x16x32_bf16 v[40:43], v[180:183], v[188:191], v[40:43]
	v_mfma_f32_16x16x32_bf16 v[32:35], v[172:175], v[196:199], v[32:35]
	v_mfma_f32_16x16x32_bf16 v[24:27], v[180:183], v[196:199], v[24:27]
	v_mfma_f32_16x16x32_bf16 v[16:19], v[172:175], v[204:207], v[16:19]
	v_mfma_f32_16x16x32_bf16 v[8:11], v[180:183], v[204:207], v[8:11]
	v_mfma_f32_16x16x32_bf16 v[4:7], v[172:175], v[212:215], v[4:7]
	v_mfma_f32_16x16x32_bf16 v[0:3], v[180:183], v[212:215], v[0:3]
	v_mfma_f32_16x16x32_bf16 v[48:51], v[176:179], v[192:195], v[48:51]
	v_mfma_f32_16x16x32_bf16 v[40:43], v[184:187], v[192:195], v[40:43]
	v_mfma_f32_16x16x32_bf16 v[32:35], v[176:179], v[200:203], v[32:35]
	v_mfma_f32_16x16x32_bf16 v[24:27], v[184:187], v[200:203], v[24:27]
	v_mfma_f32_16x16x32_bf16 v[16:19], v[176:179], v[208:211], v[16:19]
	v_mfma_f32_16x16x32_bf16 v[8:11], v[184:187], v[208:211], v[8:11]
	v_mfma_f32_16x16x32_bf16 v[4:7], v[176:179], v[216:219], v[4:7]
	v_mfma_f32_16x16x32_bf16 v[0:3], v[184:187], v[216:219], v[0:3]
	s_setprio 0
	s_barrier
	s_cmp_lg_u32 s66, 12
	s_cbranch_scc1 .Lmy_rs0_skip
	v_lshl_add_u32 v230, s26, 8, v147
	v_ashrrev_i32_e32 v231, 31, v230
	v_lshl_add_u64 v[232:233], v[230:231], 2, s[6:7]
	global_load_dword v230, v[232:233], off
	global_load_dword v234, v[232:233], off offset:128
	global_load_dword v236, v[232:233], off offset:192
	global_load_dword v238, v[232:233], off offset:512
	global_load_dword v240, v[232:233], off offset:576
	global_load_dword v242, v[232:233], off offset:640
	global_load_dword v244, v[232:233], off offset:704
	global_load_dword v232, v[232:233], off offset:64
.Lmy_rs0_skip:
	s_add_i32 s67, 0, 0x18000
	v_add_u32_e32 v136, s67, v148
	s_add_i32 s68, 0, 0x1c000
	ds_read_b128 v[154:157], v136
	ds_read_b128 v[158:161], v136 offset:1024
	ds_read_b128 v[162:165], v136 offset:2048
	ds_read_b128 v[166:169], v136 offset:3072
	v_add_u32_e32 v136, s68, v148
	ds_read_b128 v[172:175], v136
	ds_read_b128 v[176:179], v136 offset:1024
	ds_read_b128 v[180:183], v136 offset:2048
	ds_read_b128 v[184:187], v136 offset:3072
	s_add_u32 s38, s38, 0x40000
	s_addc_u32 s39, s39, 0
	s_mov_b32 m0, s47
	v_lshl_add_u64 v[228:229], s[38:39], 0, v[134:135]
	ds_read_b128 v[188:191], v152 offset:32768
	ds_read_b128 v[192:195], v152 offset:33792
	ds_read_b128 v[196:199], v152 offset:34816
	ds_read_b128 v[200:203], v152 offset:35840
	ds_read_b128 v[204:207], v152 offset:36864
	ds_read_b128 v[208:211], v152 offset:37888
	ds_read_b128 v[212:215], v152 offset:38912
	ds_read_b128 v[216:219], v152 offset:39936
	global_load_lds_dwordx4 v[228:229], off
	v_lshl_add_u64 v[228:229], s[38:39], 0, v[130:131]
	s_mov_b32 m0, s48
	s_nop 0
	global_load_lds_dwordx4 v[228:229], off
	s_cmp_lg_u32 s66, 12
	s_cbranch_scc1 .Lmy_rs0_w8
	s_waitcnt vmcnt(16)
	s_branch .Lmy_rs0_wd
.Lmy_rs0_w8:
	s_waitcnt vmcnt(8)
.Lmy_rs0_wd:
	s_waitcnt lgkmcnt(0)
	s_barrier
	s_setprio 1
	s_waitcnt lgkmcnt(0)
	v_mfma_f32_16x16x32_bf16 v[124:127], v[154:157], v[188:191], v[124:127]
	v_mfma_f32_16x16x32_bf16 v[120:123], v[162:165], v[188:191], v[120:123]
	v_mfma_f32_16x16x32_bf16 v[116:119], v[154:157], v[196:199], v[116:119]
	v_mfma_f32_16x16x32_bf16 v[112:115], v[162:165], v[196:199], v[112:115]
	v_mfma_f32_16x16x32_bf16 v[108:111], v[154:157], v[204:207], v[108:111]
	v_mfma_f32_16x16x32_bf16 v[100:103], v[162:165], v[204:207], v[100:103]
	v_mfma_f32_16x16x32_bf16 v[76:79], v[154:157], v[212:215], v[76:79]
	v_mfma_f32_16x16x32_bf16 v[72:75], v[162:165], v[212:215], v[72:75]
	v_mfma_f32_16x16x32_bf16 v[124:127], v[158:161], v[192:195], v[124:127]
	v_mfma_f32_16x16x32_bf16 v[120:123], v[166:169], v[192:195], v[120:123]
	v_mfma_f32_16x16x32_bf16 v[116:119], v[158:161], v[200:203], v[116:119]
	v_mfma_f32_16x16x32_bf16 v[112:115], v[166:169], v[200:203], v[112:115]
	v_mfma_f32_16x16x32_bf16 v[108:111], v[158:161], v[208:211], v[108:111]
	v_mfma_f32_16x16x32_bf16 v[100:103], v[166:169], v[208:211], v[100:103]
	v_mfma_f32_16x16x32_bf16 v[76:79], v[158:161], v[216:219], v[76:79]
	v_mfma_f32_16x16x32_bf16 v[72:75], v[166:169], v[216:219], v[72:75]
	s_setprio 0
	s_setprio 1
	v_mfma_f32_16x16x32_bf16 v[104:107], v[172:175], v[188:191], v[104:107]
	v_mfma_f32_16x16x32_bf16 v[96:99], v[180:183], v[188:191], v[96:99]
	v_mfma_f32_16x16x32_bf16 v[92:95], v[172:175], v[196:199], v[92:95]
	v_mfma_f32_16x16x32_bf16 v[88:91], v[180:183], v[196:199], v[88:91]
	v_mfma_f32_16x16x32_bf16 v[84:87], v[172:175], v[204:207], v[84:87]
	v_mfma_f32_16x16x32_bf16 v[80:83], v[180:183], v[204:207], v[80:83]
	v_mfma_f32_16x16x32_bf16 v[68:71], v[172:175], v[212:215], v[68:71]
	v_mfma_f32_16x16x32_bf16 v[64:67], v[180:183], v[212:215], v[64:67]
	v_mfma_f32_16x16x32_bf16 v[104:107], v[176:179], v[192:195], v[104:107]
	v_mfma_f32_16x16x32_bf16 v[96:99], v[184:187], v[192:195], v[96:99]
	v_mfma_f32_16x16x32_bf16 v[92:95], v[176:179], v[200:203], v[92:95]
	v_mfma_f32_16x16x32_bf16 v[88:91], v[184:187], v[200:203], v[88:91]
	v_mfma_f32_16x16x32_bf16 v[84:87], v[176:179], v[208:211], v[84:87]
	v_mfma_f32_16x16x32_bf16 v[80:83], v[184:187], v[208:211], v[80:83]
	v_mfma_f32_16x16x32_bf16 v[68:71], v[176:179], v[216:219], v[68:71]
	v_mfma_f32_16x16x32_bf16 v[64:67], v[184:187], v[216:219], v[64:67]
	s_setprio 0
	s_barrier
	s_add_i32 s38, s67, s43
	v_lshl_add_u64 v[220:221], v[220:221], 0, s[8:9]
	s_mov_b32 m0, s38
	ds_read_b128 v[188:191], v152 offset:49152
	ds_read_b128 v[192:195], v152 offset:50176
	ds_read_b128 v[196:199], v152 offset:51200
	ds_read_b128 v[200:203], v152 offset:52224
	ds_read_b128 v[204:207], v152 offset:53248
	ds_read_b128 v[208:211], v152 offset:54272
	ds_read_b128 v[212:215], v152 offset:55296
	ds_read_b128 v[216:219], v152 offset:56320
	global_load_lds_dwordx4 v[220:221], off
	s_add_i32 m0, s38, 0x2000
	s_add_u32 s36, s36, 0x40080
	v_lshl_add_u64 v[220:221], v[222:223], 0, s[8:9]
	s_addc_u32 s37, s37, 0
	s_add_i32 s38, s68, s43
	global_load_lds_dwordx4 v[220:221], off
	v_lshl_add_u64 v[220:221], s[36:37], 0, v[132:133]
	s_mov_b32 m0, s38
	s_nop 0
	global_load_lds_dwordx4 v[220:221], off
	v_lshl_add_u64 v[220:221], s[36:37], 0, v[128:129]
	s_add_i32 m0, s38, 0x2000
	s_nop 0
	global_load_lds_dwordx4 v[220:221], off
	v_lshl_add_u64 v[220:221], v[224:225], 0, s[8:9]
	s_mov_b32 m0, s50
	s_nop 0
	global_load_lds_dwordx4 v[220:221], off
	v_lshl_add_u64 v[220:221], v[226:227], 0, s[8:9]
	s_mov_b32 m0, s51
	s_nop 0
	global_load_lds_dwordx4 v[220:221], off
	s_waitcnt vmcnt(8)
	s_waitcnt lgkmcnt(0)
	s_barrier
	s_setprio 1
	s_waitcnt lgkmcnt(0)
	v_mfma_f32_16x16x32_bf16 v[60:63], v[154:157], v[188:191], v[60:63]
	v_mfma_f32_16x16x32_bf16 v[56:59], v[162:165], v[188:191], v[56:59]
	v_mfma_f32_16x16x32_bf16 v[52:55], v[154:157], v[196:199], v[52:55]
	v_mfma_f32_16x16x32_bf16 v[44:47], v[162:165], v[196:199], v[44:47]
	v_mfma_f32_16x16x32_bf16 v[36:39], v[154:157], v[204:207], v[36:39]
	v_mfma_f32_16x16x32_bf16 v[28:31], v[162:165], v[204:207], v[28:31]
	v_mfma_f32_16x16x32_bf16 v[20:23], v[154:157], v[212:215], v[20:23]
	v_mfma_f32_16x16x32_bf16 v[12:15], v[162:165], v[212:215], v[12:15]
	v_mfma_f32_16x16x32_bf16 v[60:63], v[158:161], v[192:195], v[60:63]
	v_mfma_f32_16x16x32_bf16 v[56:59], v[166:169], v[192:195], v[56:59]
	v_mfma_f32_16x16x32_bf16 v[52:55], v[158:161], v[200:203], v[52:55]
	v_mfma_f32_16x16x32_bf16 v[44:47], v[166:169], v[200:203], v[44:47]
	v_mfma_f32_16x16x32_bf16 v[36:39], v[158:161], v[208:211], v[36:39]
	v_mfma_f32_16x16x32_bf16 v[28:31], v[166:169], v[208:211], v[28:31]
	v_mfma_f32_16x16x32_bf16 v[20:23], v[158:161], v[216:219], v[20:23]
	v_mfma_f32_16x16x32_bf16 v[12:15], v[166:169], v[216:219], v[12:15]
	s_setprio 0
	s_setprio 1
	v_mfma_f32_16x16x32_bf16 v[48:51], v[172:175], v[188:191], v[48:51]
	v_mfma_f32_16x16x32_bf16 v[40:43], v[180:183], v[188:191], v[40:43]
	v_mfma_f32_16x16x32_bf16 v[32:35], v[172:175], v[196:199], v[32:35]
	v_mfma_f32_16x16x32_bf16 v[24:27], v[180:183], v[196:199], v[24:27]
	v_mfma_f32_16x16x32_bf16 v[16:19], v[172:175], v[204:207], v[16:19]
	v_mfma_f32_16x16x32_bf16 v[8:11], v[180:183], v[204:207], v[8:11]
	v_mfma_f32_16x16x32_bf16 v[4:7], v[172:175], v[212:215], v[4:7]
	v_mfma_f32_16x16x32_bf16 v[0:3], v[180:183], v[212:215], v[0:3]
	v_mfma_f32_16x16x32_bf16 v[48:51], v[176:179], v[192:195], v[48:51]
	v_mfma_f32_16x16x32_bf16 v[40:43], v[184:187], v[192:195], v[40:43]
	v_mfma_f32_16x16x32_bf16 v[32:35], v[176:179], v[200:203], v[32:35]
	v_mfma_f32_16x16x32_bf16 v[24:27], v[184:187], v[200:203], v[24:27]
	v_mfma_f32_16x16x32_bf16 v[16:19], v[176:179], v[208:211], v[16:19]
	v_mfma_f32_16x16x32_bf16 v[8:11], v[184:187], v[208:211], v[8:11]
	v_mfma_f32_16x16x32_bf16 v[4:7], v[176:179], v[216:219], v[4:7]
	v_mfma_f32_16x16x32_bf16 v[0:3], v[184:187], v[216:219], v[0:3]
	s_setprio 0
	s_barrier
	s_add_i32 s66, s66, 2
	s_add_u32 s34, s34, 0x100
	s_addc_u32 s35, s35, 0
	s_add_u32 s64, s64, 0x100
	s_addc_u32 s65, s65, 0
	s_cmp_gt_u32 s66, 13
	s_cbranch_scc0 .LBB0_236
	s_and_b64 vcc, exec, s[10:11]
	s_cbranch_vccz .LBB0_239
	s_barrier
.LBB0_239:
	v_lshl_add_u32 v154, s26, 8, v147
	v_ashrrev_i32_e32 v155, 31, v154
	v_lshl_add_u64 v[156:157], v[154:155], 2, s[6:7]
	v_mov_b32_e32 v158, v230
	v_mov_b32_e32 v160, v232
	v_mov_b32_e32 v162, v234
	v_mov_b32_e32 v168, v236
	v_mov_b32_e32 v174, v238
	v_mov_b32_e32 v176, v240
	v_mov_b32_e32 v178, v242
	v_mov_b32_e32 v146, v244
	s_and_b32 s19, s61, -4
	s_cmp_eq_u32 s19, 4
	s_cselect_b32 s19, s56, 0x10000000
	s_cmp_gt_u32 s61, 3
	s_cselect_b32 s19, s19, 0x8000000
	v_readlane_b32 s34, v247, 0
	v_readlane_b32 s35, v247, 1
	s_add_u32 s34, s34, s19
	s_addc_u32 s35, s35, 0
	s_lshl_b32 s19, s61, 8
	v_or_b32_e32 v164, 16, v154
	v_or_b32_e32 v166, 32, v154
	s_and_b32 s19, s19, 0x300
	v_lshlrev_b64 v[172:173], 11, v[154:155]
	v_ashrrev_i32_e32 v165, 31, v164
	v_ashrrev_i32_e32 v167, 31, v166
	v_or_b32_e32 v136, s19, v149
	v_lshlrev_b64 v[156:157], 11, v[164:165]
	v_lshlrev_b64 v[164:165], 11, v[166:167]
	v_lshl_add_u64 v[166:167], s[34:35], 0, v[172:173]
	v_lshlrev_b32_e32 v136, 1, v136
	v_lshl_add_u64 v[156:157], s[34:35], 0, v[156:157]
	v_lshl_add_u64 v[164:165], s[34:35], 0, v[164:165]
	v_lshl_add_u64 v[166:167], v[166:167], 0, v[136:137]
	v_lshl_add_u64 v[156:157], v[156:157], 0, v[136:137]
	v_lshl_add_u64 v[164:165], v[164:165], 0, v[136:137]
	v_pk_mul_f32 v[126:127], v[126:127], v[158:159] op_sel_hi:[1,0]
	v_pk_mul_f32 v[124:125], v[124:125], v[158:159] op_sel_hi:[1,0]
	v_pk_mul_f32 v[122:123], v[122:123], v[158:159] op_sel_hi:[1,0]
	v_pk_mul_f32 v[120:121], v[120:121], v[158:159] op_sel_hi:[1,0]
	v_pk_mul_f32 v[106:107], v[106:107], v[158:159] op_sel_hi:[1,0]
	v_pk_mul_f32 v[104:105], v[104:105], v[158:159] op_sel_hi:[1,0]
	v_pk_mul_f32 v[98:99], v[98:99], v[158:159] op_sel_hi:[1,0]
	v_pk_mul_f32 v[96:97], v[96:97], v[158:159] op_sel_hi:[1,0]
	v_pk_mul_f32 v[118:119], v[118:119], v[160:161] op_sel_hi:[1,0]
	v_pk_mul_f32 v[116:117], v[116:117], v[160:161] op_sel_hi:[1,0]
	v_pk_mul_f32 v[114:115], v[114:115], v[160:161] op_sel_hi:[1,0]
	v_pk_mul_f32 v[112:113], v[112:113], v[160:161] op_sel_hi:[1,0]
	v_pk_mul_f32 v[94:95], v[94:95], v[160:161] op_sel_hi:[1,0]
	v_pk_mul_f32 v[92:93], v[92:93], v[160:161] op_sel_hi:[1,0]
	v_pk_mul_f32 v[158:159], v[90:91], v[160:161] op_sel_hi:[1,0]
	v_pk_mul_f32 v[160:161], v[88:89], v[160:161] op_sel_hi:[1,0]
	v_pk_mul_f32 v[110:111], v[110:111], v[162:163] op_sel_hi:[1,0]
	v_pk_mul_f32 v[108:109], v[108:109], v[162:163] op_sel_hi:[1,0]
	v_pk_mul_f32 v[102:103], v[102:103], v[162:163] op_sel_hi:[1,0]
	v_pk_mul_f32 v[100:101], v[100:101], v[162:163] op_sel_hi:[1,0]
	v_pk_mul_f32 v[172:173], v[86:87], v[162:163] op_sel_hi:[1,0]
	v_pk_mul_f32 v[180:181], v[84:85], v[162:163] op_sel_hi:[1,0]
	v_pk_mul_f32 v[182:183], v[82:83], v[162:163] op_sel_hi:[1,0]
	v_pk_mul_f32 v[162:163], v[80:81], v[162:163] op_sel_hi:[1,0]
	v_cvt_pk_bf16_f32 v80, v124, v125
	v_cvt_pk_bf16_f32 v81, v126, v127
	v_cvt_pk_bf16_f32 v82, v120, v121
	v_cvt_pk_bf16_f32 v83, v122, v123
	v_cvt_pk_bf16_f32 v84, v104, v105
	v_cvt_pk_bf16_f32 v85, v106, v107
	v_cvt_pk_bf16_f32 v86, v96, v97
	v_cvt_pk_bf16_f32 v87, v98, v99
	v_cvt_pk_bf16_f32 v88, v116, v117
	v_cvt_pk_bf16_f32 v89, v118, v119
	v_cvt_pk_bf16_f32 v90, v112, v113
	v_cvt_pk_bf16_f32 v91, v114, v115
	v_cvt_pk_bf16_f32 v92, v92, v93
	v_cvt_pk_bf16_f32 v93, v94, v95
	v_cvt_pk_bf16_f32 v94, v160, v161
	v_cvt_pk_bf16_f32 v95, v158, v159
	v_cvt_pk_bf16_f32 v96, v108, v109
	v_cvt_pk_bf16_f32 v97, v110, v111
	v_cvt_pk_bf16_f32 v98, v100, v101
	v_cvt_pk_bf16_f32 v99, v102, v103
	global_store_dwordx4 v[166:167], v[80:83], off
	global_store_dwordx4 v[166:167], v[84:87], off offset:256
	global_store_dwordx4 v[156:157], v[88:91], off
	global_store_dwordx4 v[156:157], v[92:95], off offset:256
	global_store_dwordx4 v[164:165], v[96:99], off
	v_or_b32_e32 v80, 48, v154
	v_ashrrev_i32_e32 v81, 31, v80
	v_pk_mul_f32 v[76:77], v[76:77], v[168:169] op_sel_hi:[1,0]
	v_pk_mul_f32 v[82:83], v[74:75], v[168:169] op_sel_hi:[1,0]
	v_pk_mul_f32 v[74:75], v[72:73], v[168:169] op_sel_hi:[1,0]
	v_cvt_pk_bf16_f32 v72, v76, v77
	v_lshlrev_b64 v[76:77], 11, v[80:81]
	v_pk_mul_f32 v[78:79], v[78:79], v[168:169] op_sel_hi:[1,0]
	v_lshl_add_u64 v[76:77], s[34:35], 0, v[76:77]
	v_cvt_pk_bf16_f32 v73, v78, v79
	v_cvt_pk_bf16_f32 v74, v74, v75
	v_cvt_pk_bf16_f32 v75, v82, v83
	v_lshl_add_u64 v[76:77], v[76:77], 0, v[136:137]
	global_store_dwordx4 v[76:77], v[72:75], off
	v_pk_mul_f32 v[70:71], v[70:71], v[168:169] op_sel_hi:[1,0]
	v_pk_mul_f32 v[68:69], v[68:69], v[168:169] op_sel_hi:[1,0]
	v_pk_mul_f32 v[72:73], v[66:67], v[168:169] op_sel_hi:[1,0]
	v_pk_mul_f32 v[66:67], v[64:65], v[168:169] op_sel_hi:[1,0]
	v_cvt_pk_bf16_f32 v64, v68, v69
	v_cvt_pk_bf16_f32 v65, v70, v71
	v_cvt_pk_bf16_f32 v66, v66, v67
	v_cvt_pk_bf16_f32 v67, v72, v73
	v_pk_mul_f32 v[62:63], v[62:63], v[174:175] op_sel_hi:[1,0]
	global_store_dwordx4 v[76:77], v[64:67], off offset:256
	v_pk_mul_f32 v[60:61], v[60:61], v[174:175] op_sel_hi:[1,0]
	v_pk_mul_f32 v[50:51], v[50:51], v[174:175] op_sel_hi:[1,0]
	v_pk_mul_f32 v[64:65], v[58:59], v[174:175] op_sel_hi:[1,0]
	v_pk_mul_f32 v[58:59], v[56:57], v[174:175] op_sel_hi:[1,0]
	v_cvt_pk_bf16_f32 v57, v62, v63
	v_add_co_u32_e32 v62, vcc, s57, v166
	v_cvt_pk_bf16_f32 v56, v60, v61
	v_cvt_pk_bf16_f32 v58, v58, v59
	v_cvt_pk_bf16_f32 v59, v64, v65
	v_addc_co_u32_e32 v63, vcc, 0, v167, vcc
	global_store_dwordx4 v[62:63], v[56:59], off
	v_pk_mul_f32 v[48:49], v[48:49], v[174:175] op_sel_hi:[1,0]
	v_lshl_add_u64 v[60:61], v[166:167], 0, s[2:3]
	v_pk_mul_f32 v[56:57], v[42:43], v[174:175] op_sel_hi:[1,0]
	v_pk_mul_f32 v[42:43], v[40:41], v[174:175] op_sel_hi:[1,0]
	v_cvt_pk_bf16_f32 v40, v48, v49
	v_cvt_pk_bf16_f32 v41, v50, v51
	v_cvt_pk_bf16_f32 v42, v42, v43
	v_cvt_pk_bf16_f32 v43, v56, v57
	global_store_dwordx4 v[60:61], v[40:43], off offset:256
	v_pk_mul_f32 v[46:47], v[46:47], v[176:177] op_sel_hi:[1,0]
	v_pk_mul_f32 v[44:45], v[44:45], v[176:177] op_sel_hi:[1,0]
	v_pk_mul_f32 v[42:43], v[54:55], v[176:177] op_sel_hi:[1,0]
	v_pk_mul_f32 v[40:41], v[52:53], v[176:177] op_sel_hi:[1,0]
	v_pk_mul_f32 v[34:35], v[34:35], v[176:177] op_sel_hi:[1,0]
	v_cvt_pk_bf16_f32 v40, v40, v41
	v_cvt_pk_bf16_f32 v41, v42, v43
	v_cvt_pk_bf16_f32 v43, v46, v47
	v_add_co_u32_e32 v46, vcc, s58, v166
	v_cvt_pk_bf16_f32 v42, v44, v45
	s_nop 0
	v_addc_co_u32_e32 v47, vcc, 0, v167, vcc
	global_store_dwordx4 v[46:47], v[40:43], off
	v_pk_mul_f32 v[32:33], v[32:33], v[176:177] op_sel_hi:[1,0]
	v_lshl_add_u64 v[44:45], v[166:167], 0, s[12:13]
	v_pk_mul_f32 v[40:41], v[26:27], v[176:177] op_sel_hi:[1,0]
	v_pk_mul_f32 v[26:27], v[24:25], v[176:177] op_sel_hi:[1,0]
	v_cvt_pk_bf16_f32 v24, v32, v33
	v_cvt_pk_bf16_f32 v25, v34, v35
	v_cvt_pk_bf16_f32 v26, v26, v27
	v_cvt_pk_bf16_f32 v27, v40, v41
	global_store_dwordx4 v[44:45], v[24:27], off offset:256
	v_pk_mul_f32 v[30:31], v[30:31], v[178:179] op_sel_hi:[1,0]
	v_pk_mul_f32 v[28:29], v[28:29], v[178:179] op_sel_hi:[1,0]
	v_pk_mul_f32 v[26:27], v[38:39], v[178:179] op_sel_hi:[1,0]
	v_pk_mul_f32 v[24:25], v[36:37], v[178:179] op_sel_hi:[1,0]
	v_pk_mul_f32 v[18:19], v[18:19], v[178:179] op_sel_hi:[1,0]
	v_cvt_pk_bf16_f32 v24, v24, v25
	v_cvt_pk_bf16_f32 v25, v26, v27
	v_cvt_pk_bf16_f32 v27, v30, v31
	v_add_co_u32_e32 v30, vcc, s59, v166
	v_cvt_pk_bf16_f32 v26, v28, v29
	s_nop 0
	v_addc_co_u32_e32 v31, vcc, 0, v167, vcc
	global_store_dwordx4 v[30:31], v[24:27], off
	v_pk_mul_f32 v[16:17], v[16:17], v[178:179] op_sel_hi:[1,0]
	v_lshl_add_u64 v[28:29], v[166:167], 0, s[14:15]
	v_pk_mul_f32 v[24:25], v[10:11], v[178:179] op_sel_hi:[1,0]
	v_pk_mul_f32 v[10:11], v[8:9], v[178:179] op_sel_hi:[1,0]
	v_cvt_pk_bf16_f32 v8, v16, v17
	v_cvt_pk_bf16_f32 v9, v18, v19
	v_cvt_pk_bf16_f32 v10, v10, v11
	v_cvt_pk_bf16_f32 v11, v24, v25
	global_store_dwordx4 v[28:29], v[8:11], off offset:256
	v_pk_mul_f32 v[14:15], v[14:15], v[146:147] op_sel_hi:[1,0]
	v_pk_mul_f32 v[12:13], v[12:13], v[146:147] op_sel_hi:[1,0]
	v_pk_mul_f32 v[10:11], v[22:23], v[146:147] op_sel_hi:[1,0]
	v_pk_mul_f32 v[8:9], v[20:21], v[146:147] op_sel_hi:[1,0]
	v_pk_mul_f32 v[6:7], v[6:7], v[146:147] op_sel_hi:[1,0]
	v_cvt_pk_bf16_f32 v8, v8, v9
	v_cvt_pk_bf16_f32 v9, v10, v11
	v_cvt_pk_bf16_f32 v11, v14, v15
	v_add_co_u32_e32 v14, vcc, s60, v166
	v_cvt_pk_bf16_f32 v10, v12, v13
	s_nop 0
	v_addc_co_u32_e32 v15, vcc, 0, v167, vcc
	global_store_dwordx4 v[14:15], v[8:11], off
	v_pk_mul_f32 v[4:5], v[4:5], v[146:147] op_sel_hi:[1,0]
	v_cvt_pk_bf16_f32 v100, v180, v181
	v_pk_mul_f32 v[8:9], v[2:3], v[146:147] op_sel_hi:[1,0]
	v_pk_mul_f32 v[2:3], v[0:1], v[146:147] op_sel_hi:[1,0]
	v_cvt_pk_bf16_f32 v101, v172, v173
	v_cvt_pk_bf16_f32 v102, v162, v163
	v_cvt_pk_bf16_f32 v103, v182, v183
	v_lshl_add_u64 v[12:13], v[166:167], 0, s[16:17]
	v_cvt_pk_bf16_f32 v0, v4, v5
	v_cvt_pk_bf16_f32 v1, v6, v7
	v_cvt_pk_bf16_f32 v2, v2, v3
	v_cvt_pk_bf16_f32 v3, v8, v9
	s_andn2_b64 vcc, exec, s[0:1]
	s_mov_b64 s[0:1], -1
	global_store_dwordx4 v[164:165], v[100:103], off offset:256
	global_store_dwordx4 v[12:13], v[0:3], off offset:256
	s_cbranch_vccnz .LBB0_232
	s_andn2_b64 vcc, exec, s[4:5]
	s_cbranch_vccnz .LBB0_231
	s_barrier
	s_branch .LBB0_231

.LBB0_445:
	ds_read_b128 v[146:149], v167
	ds_read_b128 v[150:153], v167 offset:1024
	ds_read_b128 v[154:157], v167 offset:2048
	ds_read_b128 v[158:161], v167 offset:3072
	ds_read_b128 v[172:175], v168
	ds_read_b128 v[176:179], v168 offset:1024
	ds_read_b128 v[180:183], v168 offset:2048
	ds_read_b128 v[184:187], v168 offset:3072
	s_add_u32 s48, s46, 0xfffc0080
	s_addc_u32 s49, s47, -1
	s_cmp_eq_u32 s73, 12
	s_cselect_b32 s51, s1, s49
	s_cselect_b32 s50, s39, s48
	s_cselect_b32 s49, s37, s72
	s_cselect_b32 s48, s52, s53
	v_lshl_add_u64 v[162:163], s[46:47], 0, v[138:139]
	s_add_i32 m0, s45, 0xc000
	ds_read_b128 v[188:191], v169
	ds_read_b128 v[192:195], v169 offset:1024
	ds_read_b128 v[196:199], v169 offset:2048
	ds_read_b128 v[200:203], v169 offset:3072
	ds_read_b128 v[204:207], v169 offset:4096
	ds_read_b128 v[208:211], v169 offset:5120
	ds_read_b128 v[212:215], v169 offset:6144
	ds_read_b128 v[216:219], v169 offset:7168
	global_load_lds_dwordx4 v[162:163], off
	v_lshl_add_u64 v[162:163], s[46:47], 0, v[140:141]
	s_add_i32 m0, s45, 0xe000
	s_nop 0
	global_load_lds_dwordx4 v[162:163], off
	s_waitcnt vmcnt(8)
	s_waitcnt lgkmcnt(0)
	s_barrier
	s_setprio 1
	s_waitcnt lgkmcnt(0)
	v_mfma_f32_16x16x32_bf16 v[124:127], v[146:149], v[188:191], v[124:127]
	v_mfma_f32_16x16x32_bf16 v[120:123], v[154:157], v[188:191], v[120:123]
	v_mfma_f32_16x16x32_bf16 v[108:111], v[146:149], v[196:199], v[108:111]
	v_mfma_f32_16x16x32_bf16 v[104:107], v[154:157], v[196:199], v[104:107]
	v_mfma_f32_16x16x32_bf16 v[92:95], v[146:149], v[204:207], v[92:95]
	v_mfma_f32_16x16x32_bf16 v[88:91], v[154:157], v[204:207], v[88:91]
	v_mfma_f32_16x16x32_bf16 v[76:79], v[146:149], v[212:215], v[76:79]
	v_mfma_f32_16x16x32_bf16 v[72:75], v[154:157], v[212:215], v[72:75]
	v_mfma_f32_16x16x32_bf16 v[124:127], v[150:153], v[192:195], v[124:127]
	v_mfma_f32_16x16x32_bf16 v[120:123], v[158:161], v[192:195], v[120:123]
	v_mfma_f32_16x16x32_bf16 v[108:111], v[150:153], v[200:203], v[108:111]
	v_mfma_f32_16x16x32_bf16 v[104:107], v[158:161], v[200:203], v[104:107]
	v_mfma_f32_16x16x32_bf16 v[92:95], v[150:153], v[208:211], v[92:95]
	v_mfma_f32_16x16x32_bf16 v[88:91], v[158:161], v[208:211], v[88:91]
	v_mfma_f32_16x16x32_bf16 v[76:79], v[150:153], v[216:219], v[76:79]
	v_mfma_f32_16x16x32_bf16 v[72:75], v[158:161], v[216:219], v[72:75]
	s_setprio 0
	s_setprio 1
	v_mfma_f32_16x16x32_bf16 v[116:119], v[172:175], v[188:191], v[116:119]
	v_mfma_f32_16x16x32_bf16 v[112:115], v[180:183], v[188:191], v[112:115]
	v_mfma_f32_16x16x32_bf16 v[100:103], v[172:175], v[196:199], v[100:103]
	v_mfma_f32_16x16x32_bf16 v[96:99], v[180:183], v[196:199], v[96:99]
	v_mfma_f32_16x16x32_bf16 v[84:87], v[172:175], v[204:207], v[84:87]
	v_mfma_f32_16x16x32_bf16 v[80:83], v[180:183], v[204:207], v[80:83]
	v_mfma_f32_16x16x32_bf16 v[68:71], v[172:175], v[212:215], v[68:71]
	v_mfma_f32_16x16x32_bf16 v[64:67], v[180:183], v[212:215], v[64:67]
	v_mfma_f32_16x16x32_bf16 v[116:119], v[176:179], v[192:195], v[116:119]
	v_mfma_f32_16x16x32_bf16 v[112:115], v[184:187], v[192:195], v[112:115]
	v_mfma_f32_16x16x32_bf16 v[100:103], v[176:179], v[200:203], v[100:103]
	v_mfma_f32_16x16x32_bf16 v[96:99], v[184:187], v[200:203], v[96:99]
	v_mfma_f32_16x16x32_bf16 v[84:87], v[176:179], v[208:211], v[84:87]
	v_mfma_f32_16x16x32_bf16 v[80:83], v[184:187], v[208:211], v[80:83]
	v_mfma_f32_16x16x32_bf16 v[68:71], v[176:179], v[216:219], v[68:71]
	v_mfma_f32_16x16x32_bf16 v[64:67], v[184:187], v[216:219], v[64:67]
	s_setprio 0
	s_barrier
	s_add_i32 s74, s66, s57
	v_lshl_add_u64 v[162:163], s[48:49], 0, v[130:131]
	s_mov_b32 m0, s74
	ds_read_b128 v[188:191], v169 offset:16384
	ds_read_b128 v[192:195], v169 offset:17408
	ds_read_b128 v[196:199], v169 offset:18432
	ds_read_b128 v[200:203], v169 offset:19456
	ds_read_b128 v[204:207], v169 offset:20480
	ds_read_b128 v[208:211], v169 offset:21504
	ds_read_b128 v[212:215], v169 offset:22528
	ds_read_b128 v[216:219], v169 offset:23552
	global_load_lds_dwordx4 v[162:163], off
	s_add_i32 m0, s74, 0x2000
	s_add_u32 s74, s48, 0x40000
	v_lshl_add_u64 v[220:221], s[48:49], 0, v[134:135]
	s_addc_u32 s75, s49, 0
	s_add_i32 s76, s67, s57
	global_load_lds_dwordx4 v[220:221], off
	v_lshl_add_u64 v[222:223], s[74:75], 0, v[130:131]
	s_mov_b32 m0, s76
	v_lshl_add_u64 v[224:225], s[50:51], 0, v[132:133]
	global_load_lds_dwordx4 v[222:223], off
	v_lshl_add_u64 v[222:223], s[74:75], 0, v[134:135]
	s_add_i32 m0, s76, 0x2000
	s_nop 0
	global_load_lds_dwordx4 v[222:223], off
	v_lshl_add_u64 v[222:223], s[50:51], 0, v[128:129]
	s_mov_b32 m0, s45
	s_nop 0
	global_load_lds_dwordx4 v[222:223], off
	s_mov_b32 m0, s58
	s_nop 0
	global_load_lds_dwordx4 v[224:225], off
	s_waitcnt vmcnt(8)
	s_waitcnt lgkmcnt(0)
	s_barrier
	s_setprio 1
	s_waitcnt lgkmcnt(0)
	v_mfma_f32_16x16x32_bf16 v[60:63], v[146:149], v[188:191], v[60:63]
	v_mfma_f32_16x16x32_bf16 v[56:59], v[154:157], v[188:191], v[56:59]
	v_mfma_f32_16x16x32_bf16 v[44:47], v[146:149], v[196:199], v[44:47]
	v_mfma_f32_16x16x32_bf16 v[40:43], v[154:157], v[196:199], v[40:43]
	v_mfma_f32_16x16x32_bf16 v[28:31], v[146:149], v[204:207], v[28:31]
	v_mfma_f32_16x16x32_bf16 v[24:27], v[154:157], v[204:207], v[24:27]
	v_mfma_f32_16x16x32_bf16 v[12:15], v[146:149], v[212:215], v[12:15]
	v_mfma_f32_16x16x32_bf16 v[8:11], v[154:157], v[212:215], v[8:11]
	v_mfma_f32_16x16x32_bf16 v[60:63], v[150:153], v[192:195], v[60:63]
	v_mfma_f32_16x16x32_bf16 v[56:59], v[158:161], v[192:195], v[56:59]
	v_mfma_f32_16x16x32_bf16 v[44:47], v[150:153], v[200:203], v[44:47]
	v_mfma_f32_16x16x32_bf16 v[40:43], v[158:161], v[200:203], v[40:43]
	v_mfma_f32_16x16x32_bf16 v[28:31], v[150:153], v[208:211], v[28:31]
	v_mfma_f32_16x16x32_bf16 v[24:27], v[158:161], v[208:211], v[24:27]
	v_mfma_f32_16x16x32_bf16 v[12:15], v[150:153], v[216:219], v[12:15]
	v_mfma_f32_16x16x32_bf16 v[8:11], v[158:161], v[216:219], v[8:11]
	s_setprio 0
	s_setprio 1
	v_mfma_f32_16x16x32_bf16 v[52:55], v[172:175], v[188:191], v[52:55]
	v_mfma_f32_16x16x32_bf16 v[48:51], v[180:183], v[188:191], v[48:51]
	v_mfma_f32_16x16x32_bf16 v[36:39], v[172:175], v[196:199], v[36:39]
	v_mfma_f32_16x16x32_bf16 v[32:35], v[180:183], v[196:199], v[32:35]
	v_mfma_f32_16x16x32_bf16 v[20:23], v[172:175], v[204:207], v[20:23]
	v_mfma_f32_16x16x32_bf16 v[16:19], v[180:183], v[204:207], v[16:19]
	v_mfma_f32_16x16x32_bf16 v[4:7], v[172:175], v[212:215], v[4:7]
	v_mfma_f32_16x16x32_bf16 v[0:3], v[180:183], v[212:215], v[0:3]
	v_mfma_f32_16x16x32_bf16 v[52:55], v[176:179], v[192:195], v[52:55]
	v_mfma_f32_16x16x32_bf16 v[48:51], v[184:187], v[192:195], v[48:51]
	v_mfma_f32_16x16x32_bf16 v[36:39], v[176:179], v[200:203], v[36:39]
	v_mfma_f32_16x16x32_bf16 v[32:35], v[184:187], v[200:203], v[32:35]
	v_mfma_f32_16x16x32_bf16 v[20:23], v[176:179], v[208:211], v[20:23]
	v_mfma_f32_16x16x32_bf16 v[16:19], v[184:187], v[208:211], v[16:19]
	v_mfma_f32_16x16x32_bf16 v[4:7], v[176:179], v[216:219], v[4:7]
	v_mfma_f32_16x16x32_bf16 v[0:3], v[184:187], v[216:219], v[0:3]
	s_setprio 0
	s_barrier
	s_cmp_lg_u32 s73, 12
	s_cbranch_scc1 .Lmy_rs5_skip
	v_lshl_add_u32 v230, s0, 8, v164
	v_ashrrev_i32_e32 v231, 31, v230
	v_lshl_add_u64 v[232:233], v[230:231], 2, s[16:17]
	global_load_dword v230, v[232:233], off
	global_load_dword v234, v[232:233], off offset:128
	global_load_dword v236, v[232:233], off offset:192
	global_load_dword v238, v[232:233], off offset:512
	global_load_dword v240, v[232:233], off offset:576
	global_load_dword v242, v[232:233], off offset:640
	global_load_dword v244, v[232:233], off offset:704
	global_load_dword v232, v[232:233], off offset:64
.Lmy_rs5_skip:
	s_add_i32 s74, 0, 0x18000
	v_add_u32_e32 v136, s74, v165
	s_add_i32 s75, 0, 0x1c000
	ds_read_b128 v[146:149], v136
	ds_read_b128 v[150:153], v136 offset:1024
	ds_read_b128 v[154:157], v136 offset:2048
	ds_read_b128 v[158:161], v136 offset:3072
	v_add_u32_e32 v136, s75, v165
	ds_read_b128 v[172:175], v136
	ds_read_b128 v[176:179], v136 offset:1024
	ds_read_b128 v[180:183], v136 offset:2048
	ds_read_b128 v[184:187], v136 offset:3072
	s_add_u32 s50, s50, 0x40000
	s_addc_u32 s51, s51, 0
	s_mov_b32 m0, s59
	v_lshl_add_u64 v[226:227], s[50:51], 0, v[128:129]
	ds_read_b128 v[188:191], v169 offset:32768
	ds_read_b128 v[192:195], v169 offset:33792
	ds_read_b128 v[196:199], v169 offset:34816
	ds_read_b128 v[200:203], v169 offset:35840
	ds_read_b128 v[204:207], v169 offset:36864
	ds_read_b128 v[208:211], v169 offset:37888
	ds_read_b128 v[212:215], v169 offset:38912
	ds_read_b128 v[216:219], v169 offset:39936
	global_load_lds_dwordx4 v[226:227], off
	v_lshl_add_u64 v[226:227], s[50:51], 0, v[132:133]
	s_mov_b32 m0, s60
	s_nop 0
	global_load_lds_dwordx4 v[226:227], off
	s_cmp_lg_u32 s73, 12
	s_cbranch_scc1 .Lmy_rs5_w8
	s_waitcnt vmcnt(16)
	s_branch .Lmy_rs5_wd

.Lmy_rs5_wd:
	s_waitcnt lgkmcnt(0)
	s_barrier
	s_setprio 1
	s_waitcnt lgkmcnt(0)
	v_mfma_f32_16x16x32_bf16 v[124:127], v[146:149], v[188:191], v[124:127]
	v_mfma_f32_16x16x32_bf16 v[120:123], v[154:157], v[188:191], v[120:123]
	v_mfma_f32_16x16x32_bf16 v[108:111], v[146:149], v[196:199], v[108:111]
	v_mfma_f32_16x16x32_bf16 v[104:107], v[154:157], v[196:199], v[104:107]
	v_mfma_f32_16x16x32_bf16 v[92:95], v[146:149], v[204:207], v[92:95]
	v_mfma_f32_16x16x32_bf16 v[88:91], v[154:157], v[204:207], v[88:91]
	v_mfma_f32_16x16x32_bf16 v[76:79], v[146:149], v[212:215], v[76:79]
	v_mfma_f32_16x16x32_bf16 v[72:75], v[154:157], v[212:215], v[72:75]
	v_mfma_f32_16x16x32_bf16 v[124:127], v[150:153], v[192:195], v[124:127]
	v_mfma_f32_16x16x32_bf16 v[120:123], v[158:161], v[192:195], v[120:123]
	v_mfma_f32_16x16x32_bf16 v[108:111], v[150:153], v[200:203], v[108:111]
	v_mfma_f32_16x16x32_bf16 v[104:107], v[158:161], v[200:203], v[104:107]
	v_mfma_f32_16x16x32_bf16 v[92:95], v[150:153], v[208:211], v[92:95]
	v_mfma_f32_16x16x32_bf16 v[88:91], v[158:161], v[208:211], v[88:91]
	v_mfma_f32_16x16x32_bf16 v[76:79], v[150:153], v[216:219], v[76:79]
	v_mfma_f32_16x16x32_bf16 v[72:75], v[158:161], v[216:219], v[72:75]
	s_setprio 0
	s_setprio 1
	v_mfma_f32_16x16x32_bf16 v[116:119], v[172:175], v[188:191], v[116:119]
	v_mfma_f32_16x16x32_bf16 v[112:115], v[180:183], v[188:191], v[112:115]
	v_mfma_f32_16x16x32_bf16 v[100:103], v[172:175], v[196:199], v[100:103]
	v_mfma_f32_16x16x32_bf16 v[96:99], v[180:183], v[196:199], v[96:99]
	v_mfma_f32_16x16x32_bf16 v[84:87], v[172:175], v[204:207], v[84:87]
	v_mfma_f32_16x16x32_bf16 v[80:83], v[180:183], v[204:207], v[80:83]
	v_mfma_f32_16x16x32_bf16 v[68:71], v[172:175], v[212:215], v[68:71]
	v_mfma_f32_16x16x32_bf16 v[64:67], v[180:183], v[212:215], v[64:67]
	v_mfma_f32_16x16x32_bf16 v[116:119], v[176:179], v[192:195], v[116:119]
	v_mfma_f32_16x16x32_bf16 v[112:115], v[184:187], v[192:195], v[112:115]
	v_mfma_f32_16x16x32_bf16 v[100:103], v[176:179], v[200:203], v[100:103]
	v_mfma_f32_16x16x32_bf16 v[96:99], v[184:187], v[200:203], v[96:99]
	v_mfma_f32_16x16x32_bf16 v[84:87], v[176:179], v[208:211], v[84:87]
	v_mfma_f32_16x16x32_bf16 v[80:83], v[184:187], v[208:211], v[80:83]
	v_mfma_f32_16x16x32_bf16 v[68:71], v[176:179], v[216:219], v[68:71]
	v_mfma_f32_16x16x32_bf16 v[64:67], v[184:187], v[216:219], v[64:67]
	s_setprio 0
	s_barrier
	s_add_i32 s50, s74, s57
	v_lshl_add_u64 v[162:163], v[162:163], 0, s[18:19]
	s_mov_b32 m0, s50
	ds_read_b128 v[188:191], v169 offset:49152
	ds_read_b128 v[192:195], v169 offset:50176
	ds_read_b128 v[196:199], v169 offset:51200
	ds_read_b128 v[200:203], v169 offset:52224
	ds_read_b128 v[204:207], v169 offset:53248
	ds_read_b128 v[208:211], v169 offset:54272
	ds_read_b128 v[212:215], v169 offset:55296
	ds_read_b128 v[216:219], v169 offset:56320
	global_load_lds_dwordx4 v[162:163], off
	s_add_i32 m0, s50, 0x2000
	s_add_u32 s48, s48, 0x40080
	v_lshl_add_u64 v[162:163], v[220:221], 0, s[18:19]
	s_addc_u32 s49, s49, 0
	s_add_i32 s50, s75, s57
	global_load_lds_dwordx4 v[162:163], off
	v_lshl_add_u64 v[162:163], s[48:49], 0, v[130:131]
	s_mov_b32 m0, s50
	s_nop 0
	global_load_lds_dwordx4 v[162:163], off
	v_lshl_add_u64 v[162:163], s[48:49], 0, v[134:135]
	s_add_i32 m0, s50, 0x2000
	s_nop 0
	global_load_lds_dwordx4 v[162:163], off
	v_lshl_add_u64 v[162:163], v[222:223], 0, s[18:19]
	s_mov_b32 m0, s33
	s_nop 0
	global_load_lds_dwordx4 v[162:163], off
	v_lshl_add_u64 v[162:163], v[224:225], 0, s[18:19]
	s_mov_b32 m0, s62
	s_nop 0
	global_load_lds_dwordx4 v[162:163], off
	s_waitcnt vmcnt(8)
	s_waitcnt lgkmcnt(0)
	s_barrier
	s_setprio 1
	s_waitcnt lgkmcnt(0)
	v_mfma_f32_16x16x32_bf16 v[60:63], v[146:149], v[188:191], v[60:63]
	v_mfma_f32_16x16x32_bf16 v[56:59], v[154:157], v[188:191], v[56:59]
	v_mfma_f32_16x16x32_bf16 v[44:47], v[146:149], v[196:199], v[44:47]
	v_mfma_f32_16x16x32_bf16 v[40:43], v[154:157], v[196:199], v[40:43]
	v_mfma_f32_16x16x32_bf16 v[28:31], v[146:149], v[204:207], v[28:31]
	v_mfma_f32_16x16x32_bf16 v[24:27], v[154:157], v[204:207], v[24:27]
	v_mfma_f32_16x16x32_bf16 v[12:15], v[146:149], v[212:215], v[12:15]
	v_mfma_f32_16x16x32_bf16 v[8:11], v[154:157], v[212:215], v[8:11]
	v_mfma_f32_16x16x32_bf16 v[60:63], v[150:153], v[192:195], v[60:63]
	v_mfma_f32_16x16x32_bf16 v[56:59], v[158:161], v[192:195], v[56:59]
	v_mfma_f32_16x16x32_bf16 v[44:47], v[150:153], v[200:203], v[44:47]
	v_mfma_f32_16x16x32_bf16 v[40:43], v[158:161], v[200:203], v[40:43]
	v_mfma_f32_16x16x32_bf16 v[28:31], v[150:153], v[208:211], v[28:31]
	v_mfma_f32_16x16x32_bf16 v[24:27], v[158:161], v[208:211], v[24:27]
	v_mfma_f32_16x16x32_bf16 v[12:15], v[150:153], v[216:219], v[12:15]
	v_mfma_f32_16x16x32_bf16 v[8:11], v[158:161], v[216:219], v[8:11]
	s_setprio 0
	s_setprio 1
	v_mfma_f32_16x16x32_bf16 v[52:55], v[172:175], v[188:191], v[52:55]
	v_mfma_f32_16x16x32_bf16 v[48:51], v[180:183], v[188:191], v[48:51]
	v_mfma_f32_16x16x32_bf16 v[36:39], v[172:175], v[196:199], v[36:39]
	v_mfma_f32_16x16x32_bf16 v[32:35], v[180:183], v[196:199], v[32:35]
	v_mfma_f32_16x16x32_bf16 v[20:23], v[172:175], v[204:207], v[20:23]
	v_mfma_f32_16x16x32_bf16 v[16:19], v[180:183], v[204:207], v[16:19]
	v_mfma_f32_16x16x32_bf16 v[4:7], v[172:175], v[212:215], v[4:7]
	v_mfma_f32_16x16x32_bf16 v[0:3], v[180:183], v[212:215], v[0:3]
	v_mfma_f32_16x16x32_bf16 v[52:55], v[176:179], v[192:195], v[52:55]
	v_mfma_f32_16x16x32_bf16 v[48:51], v[184:187], v[192:195], v[48:51]
	v_mfma_f32_16x16x32_bf16 v[36:39], v[176:179], v[200:203], v[36:39]
	v_mfma_f32_16x16x32_bf16 v[32:35], v[184:187], v[200:203], v[32:35]
	v_mfma_f32_16x16x32_bf16 v[20:23], v[176:179], v[208:211], v[20:23]
	v_mfma_f32_16x16x32_bf16 v[16:19], v[184:187], v[208:211], v[16:19]
	v_mfma_f32_16x16x32_bf16 v[4:7], v[176:179], v[216:219], v[4:7]
	v_mfma_f32_16x16x32_bf16 v[0:3], v[184:187], v[216:219], v[0:3]
	s_setprio 0
	s_barrier
	s_add_i32 s73, s73, 2
	s_add_u32 s46, s46, 0x100
	s_addc_u32 s47, s47, 0
	s_add_u32 s53, s53, 0x100
	s_addc_u32 s72, s72, 0
	s_cmp_gt_u32 s73, 13
	s_cbranch_scc0 .LBB0_445
	s_and_b64 vcc, exec, s[20:21]
	s_cbranch_vccz .LBB0_448
	s_barrier

.LBB0_461:
	v_lshl_add_u32 v154, s0, 8, v164
	v_ashrrev_i32_e32 v155, 31, v154
	v_lshl_add_u64 v[146:147], v[154:155], 2, s[16:17]
	v_mov_b32_e32 v162, v230
	v_mov_b32_e32 v160, v232
	v_mov_b32_e32 v158, v234
	v_mov_b32_e32 v156, v236
	v_mov_b32_e32 v152, v238
	v_mov_b32_e32 v150, v240
	v_mov_b32_e32 v148, v242
	v_mov_b32_e32 v146, v244
	v_cndmask_b32_e64 v136, 0, 1, s[48:49]
	v_cmp_ne_u32_e64 s[0:1], 1, v136
	s_andn2_b64 vcc, exec, s[48:49]
	v_pk_mul_f32 v[126:127], v[126:127], v[162:163] op_sel_hi:[1,0]
	v_pk_mul_f32 v[124:125], v[124:125], v[162:163] op_sel_hi:[1,0]
	v_pk_mul_f32 v[122:123], v[122:123], v[162:163] op_sel_hi:[1,0]
	v_pk_mul_f32 v[120:121], v[120:121], v[162:163] op_sel_hi:[1,0]
	s_cbranch_vccnz .LBB0_463
	v_pk_mul_f32 v[172:173], v[126:127], s[22:23] op_sel_hi:[1,0]
	v_pk_mul_f32 v[174:175], v[124:125], s[22:23] op_sel_hi:[1,0]
	v_pk_mul_f32 v[176:177], v[122:123], s[22:23] op_sel_hi:[1,0]
	v_pk_mul_f32 v[178:179], v[120:121], s[22:23] op_sel_hi:[1,0]
	v_exp_f32_e32 v174, v174
	v_exp_f32_e32 v172, v172
	v_exp_f32_e32 v173, v173
	v_exp_f32_e32 v175, v175
	v_exp_f32_e32 v178, v178
	v_exp_f32_e32 v176, v176
	v_exp_f32_e32 v177, v177
	v_exp_f32_e32 v179, v179
	v_pk_add_f32 v[172:173], v[172:173], 1.0 op_sel_hi:[1,0]
	v_pk_add_f32 v[174:175], v[174:175], 1.0 op_sel_hi:[1,0]
	v_pk_add_f32 v[176:177], v[176:177], 1.0 op_sel_hi:[1,0]
	v_pk_add_f32 v[178:179], v[178:179], 1.0 op_sel_hi:[1,0]
	v_rcp_f32_e32 v174, v174
	v_rcp_f32_e32 v175, v175
	v_rcp_f32_e32 v172, v172
	v_rcp_f32_e32 v173, v173
	v_rcp_f32_e32 v178, v178
	v_rcp_f32_e32 v176, v176
	v_rcp_f32_e32 v177, v177
	v_rcp_f32_e32 v179, v179
	v_pk_mul_f32 v[126:127], v[126:127], v[172:173]
	v_pk_mul_f32 v[124:125], v[124:125], v[174:175]
	v_pk_mul_f32 v[122:123], v[122:123], v[176:177]
	v_pk_mul_f32 v[120:121], v[120:121], v[178:179]

.LBB0_771:
	ds_read_b128 v[144:147], v174
	ds_read_b128 v[148:151], v174 offset:1024
	ds_read_b128 v[152:155], v174 offset:2048
	ds_read_b128 v[156:159], v174 offset:3072
	ds_read_b128 v[160:163], v175
	ds_read_b128 v[164:167], v175 offset:1024
	ds_read_b128 v[178:181], v175 offset:2048
	ds_read_b128 v[182:185], v175 offset:3072
	s_add_u32 s48, s46, 0xfffc0080
	s_addc_u32 s49, s47, -1
	s_cmp_eq_u32 s71, 12
	s_cselect_b32 s51, s1, s49
	s_cselect_b32 s50, s7, s48
	s_cselect_b32 s49, s33, s70
	s_cselect_b32 s48, s39, s41
	v_lshl_add_u64 v[168:169], s[46:47], 0, v[136:137]
	s_add_i32 m0, s56, 0xc000
	ds_read_b128 v[186:189], v176
	ds_read_b128 v[190:193], v176 offset:1024
	ds_read_b128 v[194:197], v176 offset:2048
	ds_read_b128 v[198:201], v176 offset:3072
	ds_read_b128 v[202:205], v176 offset:4096
	ds_read_b128 v[206:209], v176 offset:5120
	ds_read_b128 v[210:213], v176 offset:6144
	ds_read_b128 v[214:217], v176 offset:7168
	global_load_lds_dwordx4 v[168:169], off
	v_lshl_add_u64 v[168:169], s[46:47], 0, v[138:139]
	s_add_i32 m0, s56, 0xe000
	s_nop 0
	global_load_lds_dwordx4 v[168:169], off
	s_waitcnt vmcnt(8)
	s_waitcnt lgkmcnt(0)
	s_barrier
	s_setprio 1
	s_waitcnt lgkmcnt(0)
	v_mfma_f32_16x16x32_bf16 v[124:127], v[144:147], v[186:189], v[124:127]
	v_mfma_f32_16x16x32_bf16 v[120:123], v[152:155], v[186:189], v[120:123]
	v_mfma_f32_16x16x32_bf16 v[108:111], v[144:147], v[194:197], v[108:111]
	v_mfma_f32_16x16x32_bf16 v[104:107], v[152:155], v[194:197], v[104:107]
	v_mfma_f32_16x16x32_bf16 v[92:95], v[144:147], v[202:205], v[92:95]
	v_mfma_f32_16x16x32_bf16 v[88:91], v[152:155], v[202:205], v[88:91]
	v_mfma_f32_16x16x32_bf16 v[76:79], v[144:147], v[210:213], v[76:79]
	v_mfma_f32_16x16x32_bf16 v[72:75], v[152:155], v[210:213], v[72:75]
	v_mfma_f32_16x16x32_bf16 v[124:127], v[148:151], v[190:193], v[124:127]
	v_mfma_f32_16x16x32_bf16 v[120:123], v[156:159], v[190:193], v[120:123]
	v_mfma_f32_16x16x32_bf16 v[108:111], v[148:151], v[198:201], v[108:111]
	v_mfma_f32_16x16x32_bf16 v[104:107], v[156:159], v[198:201], v[104:107]
	v_mfma_f32_16x16x32_bf16 v[92:95], v[148:151], v[206:209], v[92:95]
	v_mfma_f32_16x16x32_bf16 v[88:91], v[156:159], v[206:209], v[88:91]
	v_mfma_f32_16x16x32_bf16 v[76:79], v[148:151], v[214:217], v[76:79]
	v_mfma_f32_16x16x32_bf16 v[72:75], v[156:159], v[214:217], v[72:75]
	s_setprio 0
	s_setprio 1
	v_mfma_f32_16x16x32_bf16 v[116:119], v[160:163], v[186:189], v[116:119]
	v_mfma_f32_16x16x32_bf16 v[112:115], v[178:181], v[186:189], v[112:115]
	v_mfma_f32_16x16x32_bf16 v[100:103], v[160:163], v[194:197], v[100:103]
	v_mfma_f32_16x16x32_bf16 v[96:99], v[178:181], v[194:197], v[96:99]
	v_mfma_f32_16x16x32_bf16 v[84:87], v[160:163], v[202:205], v[84:87]
	v_mfma_f32_16x16x32_bf16 v[80:83], v[178:181], v[202:205], v[80:83]
	v_mfma_f32_16x16x32_bf16 v[68:71], v[160:163], v[210:213], v[68:71]
	v_mfma_f32_16x16x32_bf16 v[64:67], v[178:181], v[210:213], v[64:67]
	v_mfma_f32_16x16x32_bf16 v[116:119], v[164:167], v[190:193], v[116:119]
	v_mfma_f32_16x16x32_bf16 v[112:115], v[182:185], v[190:193], v[112:115]
	v_mfma_f32_16x16x32_bf16 v[100:103], v[164:167], v[198:201], v[100:103]
	v_mfma_f32_16x16x32_bf16 v[96:99], v[182:185], v[198:201], v[96:99]
	v_mfma_f32_16x16x32_bf16 v[84:87], v[164:167], v[206:209], v[84:87]
	v_mfma_f32_16x16x32_bf16 v[80:83], v[182:185], v[206:209], v[80:83]
	v_mfma_f32_16x16x32_bf16 v[68:71], v[164:167], v[214:217], v[68:71]
	v_mfma_f32_16x16x32_bf16 v[64:67], v[182:185], v[214:217], v[64:67]
	s_setprio 0
	s_barrier
	s_add_i32 s72, s67, s55
	v_lshl_add_u64 v[168:169], s[48:49], 0, v[130:131]
	s_mov_b32 m0, s72
	ds_read_b128 v[186:189], v176 offset:16384
	ds_read_b128 v[190:193], v176 offset:17408
	ds_read_b128 v[194:197], v176 offset:18432
	ds_read_b128 v[198:201], v176 offset:19456
	ds_read_b128 v[202:205], v176 offset:20480
	ds_read_b128 v[206:209], v176 offset:21504
	ds_read_b128 v[210:213], v176 offset:22528
	ds_read_b128 v[214:217], v176 offset:23552
	global_load_lds_dwordx4 v[168:169], off
	s_add_i32 m0, s72, 0x2000
	s_add_u32 s72, s48, 0x40000
	v_lshl_add_u64 v[218:219], s[48:49], 0, v[134:135]
	s_addc_u32 s73, s49, 0
	s_add_i32 s74, s68, s55
	global_load_lds_dwordx4 v[218:219], off
	v_lshl_add_u64 v[220:221], s[72:73], 0, v[130:131]
	s_mov_b32 m0, s74
	v_lshl_add_u64 v[222:223], s[50:51], 0, v[132:133]
	global_load_lds_dwordx4 v[220:221], off
	v_lshl_add_u64 v[220:221], s[72:73], 0, v[134:135]
	s_add_i32 m0, s74, 0x2000
	s_nop 0
	global_load_lds_dwordx4 v[220:221], off
	v_lshl_add_u64 v[220:221], s[50:51], 0, v[128:129]
	s_mov_b32 m0, s56
	s_nop 0
	global_load_lds_dwordx4 v[220:221], off
	s_mov_b32 m0, s57
	s_nop 0
	global_load_lds_dwordx4 v[222:223], off
	s_waitcnt vmcnt(8)
	s_waitcnt lgkmcnt(0)
	s_barrier
	s_setprio 1
	s_waitcnt lgkmcnt(0)
	v_mfma_f32_16x16x32_bf16 v[60:63], v[144:147], v[186:189], v[60:63]
	v_mfma_f32_16x16x32_bf16 v[56:59], v[152:155], v[186:189], v[56:59]
	v_mfma_f32_16x16x32_bf16 v[44:47], v[144:147], v[194:197], v[44:47]
	v_mfma_f32_16x16x32_bf16 v[40:43], v[152:155], v[194:197], v[40:43]
	v_mfma_f32_16x16x32_bf16 v[28:31], v[144:147], v[202:205], v[28:31]
	v_mfma_f32_16x16x32_bf16 v[24:27], v[152:155], v[202:205], v[24:27]
	v_mfma_f32_16x16x32_bf16 v[12:15], v[144:147], v[210:213], v[12:15]
	v_mfma_f32_16x16x32_bf16 v[8:11], v[152:155], v[210:213], v[8:11]
	v_mfma_f32_16x16x32_bf16 v[60:63], v[148:151], v[190:193], v[60:63]
	v_mfma_f32_16x16x32_bf16 v[56:59], v[156:159], v[190:193], v[56:59]
	v_mfma_f32_16x16x32_bf16 v[44:47], v[148:151], v[198:201], v[44:47]
	v_mfma_f32_16x16x32_bf16 v[40:43], v[156:159], v[198:201], v[40:43]
	v_mfma_f32_16x16x32_bf16 v[28:31], v[148:151], v[206:209], v[28:31]
	v_mfma_f32_16x16x32_bf16 v[24:27], v[156:159], v[206:209], v[24:27]
	v_mfma_f32_16x16x32_bf16 v[12:15], v[148:151], v[214:217], v[12:15]
	v_mfma_f32_16x16x32_bf16 v[8:11], v[156:159], v[214:217], v[8:11]
	s_setprio 0
	s_setprio 1
	v_mfma_f32_16x16x32_bf16 v[52:55], v[160:163], v[186:189], v[52:55]
	v_mfma_f32_16x16x32_bf16 v[48:51], v[178:181], v[186:189], v[48:51]
	v_mfma_f32_16x16x32_bf16 v[36:39], v[160:163], v[194:197], v[36:39]
	v_mfma_f32_16x16x32_bf16 v[32:35], v[178:181], v[194:197], v[32:35]
	v_mfma_f32_16x16x32_bf16 v[20:23], v[160:163], v[202:205], v[20:23]
	v_mfma_f32_16x16x32_bf16 v[16:19], v[178:181], v[202:205], v[16:19]
	v_mfma_f32_16x16x32_bf16 v[4:7], v[160:163], v[210:213], v[4:7]
	v_mfma_f32_16x16x32_bf16 v[0:3], v[178:181], v[210:213], v[0:3]
	v_mfma_f32_16x16x32_bf16 v[52:55], v[164:167], v[190:193], v[52:55]
	v_mfma_f32_16x16x32_bf16 v[48:51], v[182:185], v[190:193], v[48:51]
	v_mfma_f32_16x16x32_bf16 v[36:39], v[164:167], v[198:201], v[36:39]
	v_mfma_f32_16x16x32_bf16 v[32:35], v[182:185], v[198:201], v[32:35]
	v_mfma_f32_16x16x32_bf16 v[20:23], v[164:167], v[206:209], v[20:23]
	v_mfma_f32_16x16x32_bf16 v[16:19], v[182:185], v[206:209], v[16:19]
	v_mfma_f32_16x16x32_bf16 v[4:7], v[164:167], v[214:217], v[4:7]
	v_mfma_f32_16x16x32_bf16 v[0:3], v[182:185], v[214:217], v[0:3]
	s_setprio 0
	s_barrier
	s_cmp_lg_u32 s71, 12
	s_cbranch_scc1 .Lmy_rs8_skip
	v_lshl_add_u32 v230, s6, 8, v171
	v_ashrrev_i32_e32 v231, 31, v230
	v_lshl_add_u64 v[232:233], v[230:231], 2, s[12:13]
	global_load_dword v230, v[232:233], off
	global_load_dword v234, v[232:233], off offset:128
	global_load_dword v236, v[232:233], off offset:192
	global_load_dword v238, v[232:233], off offset:512
	global_load_dword v240, v[232:233], off offset:576
	global_load_dword v242, v[232:233], off offset:640
	global_load_dword v244, v[232:233], off offset:704
	global_load_dword v232, v[232:233], off offset:64
.Lmy_rs8_skip:
	s_add_i32 s72, 0, 0x18000
	s_add_i32 s73, 0, 0x1c000
	v_add_u32_e32 v156, s72, v172
	v_add_u32_e32 v182, s73, v172
	ds_read_b128 v[144:147], v156
	ds_read_b128 v[148:151], v156 offset:1024
	ds_read_b128 v[152:155], v156 offset:2048
	ds_read_b128 v[156:159], v156 offset:3072
	ds_read_b128 v[160:163], v182
	ds_read_b128 v[164:167], v182 offset:1024
	ds_read_b128 v[178:181], v182 offset:2048
	ds_read_b128 v[182:185], v182 offset:3072
	s_add_u32 s50, s50, 0x40000
	s_addc_u32 s51, s51, 0
	s_mov_b32 m0, s58
	v_lshl_add_u64 v[224:225], s[50:51], 0, v[128:129]
	ds_read_b128 v[186:189], v176 offset:32768
	ds_read_b128 v[190:193], v176 offset:33792
	ds_read_b128 v[194:197], v176 offset:34816
	ds_read_b128 v[198:201], v176 offset:35840
	ds_read_b128 v[202:205], v176 offset:36864
	ds_read_b128 v[206:209], v176 offset:37888
	ds_read_b128 v[210:213], v176 offset:38912
	ds_read_b128 v[214:217], v176 offset:39936
	global_load_lds_dwordx4 v[224:225], off
	v_lshl_add_u64 v[224:225], s[50:51], 0, v[132:133]
	s_mov_b32 m0, s59
	s_nop 0
	global_load_lds_dwordx4 v[224:225], off
	s_cmp_lg_u32 s71, 12
	s_cbranch_scc1 .Lmy_rs8_w8
	s_waitcnt vmcnt(16)
	s_branch .Lmy_rs8_wd

.Lmy_rs8_wd:
	s_waitcnt lgkmcnt(0)
	s_barrier
	s_setprio 1
	s_waitcnt lgkmcnt(0)
	v_mfma_f32_16x16x32_bf16 v[124:127], v[144:147], v[186:189], v[124:127]
	v_mfma_f32_16x16x32_bf16 v[120:123], v[152:155], v[186:189], v[120:123]
	v_mfma_f32_16x16x32_bf16 v[108:111], v[144:147], v[194:197], v[108:111]
	v_mfma_f32_16x16x32_bf16 v[104:107], v[152:155], v[194:197], v[104:107]
	v_mfma_f32_16x16x32_bf16 v[92:95], v[144:147], v[202:205], v[92:95]
	v_mfma_f32_16x16x32_bf16 v[88:91], v[152:155], v[202:205], v[88:91]
	v_mfma_f32_16x16x32_bf16 v[76:79], v[144:147], v[210:213], v[76:79]
	v_mfma_f32_16x16x32_bf16 v[72:75], v[152:155], v[210:213], v[72:75]
	v_mfma_f32_16x16x32_bf16 v[124:127], v[148:151], v[190:193], v[124:127]
	v_mfma_f32_16x16x32_bf16 v[120:123], v[156:159], v[190:193], v[120:123]
	v_mfma_f32_16x16x32_bf16 v[108:111], v[148:151], v[198:201], v[108:111]
	v_mfma_f32_16x16x32_bf16 v[104:107], v[156:159], v[198:201], v[104:107]
	v_mfma_f32_16x16x32_bf16 v[92:95], v[148:151], v[206:209], v[92:95]
	v_mfma_f32_16x16x32_bf16 v[88:91], v[156:159], v[206:209], v[88:91]
	v_mfma_f32_16x16x32_bf16 v[76:79], v[148:151], v[214:217], v[76:79]
	v_mfma_f32_16x16x32_bf16 v[72:75], v[156:159], v[214:217], v[72:75]
	s_setprio 0
	s_setprio 1
	v_mfma_f32_16x16x32_bf16 v[116:119], v[160:163], v[186:189], v[116:119]
	v_mfma_f32_16x16x32_bf16 v[112:115], v[178:181], v[186:189], v[112:115]
	v_mfma_f32_16x16x32_bf16 v[100:103], v[160:163], v[194:197], v[100:103]
	v_mfma_f32_16x16x32_bf16 v[96:99], v[178:181], v[194:197], v[96:99]
	v_mfma_f32_16x16x32_bf16 v[84:87], v[160:163], v[202:205], v[84:87]
	v_mfma_f32_16x16x32_bf16 v[80:83], v[178:181], v[202:205], v[80:83]
	v_mfma_f32_16x16x32_bf16 v[68:71], v[160:163], v[210:213], v[68:71]
	v_mfma_f32_16x16x32_bf16 v[64:67], v[178:181], v[210:213], v[64:67]
	v_mfma_f32_16x16x32_bf16 v[116:119], v[164:167], v[190:193], v[116:119]
	v_mfma_f32_16x16x32_bf16 v[112:115], v[182:185], v[190:193], v[112:115]
	v_mfma_f32_16x16x32_bf16 v[100:103], v[164:167], v[198:201], v[100:103]
	v_mfma_f32_16x16x32_bf16 v[96:99], v[182:185], v[198:201], v[96:99]
	v_mfma_f32_16x16x32_bf16 v[84:87], v[164:167], v[206:209], v[84:87]
	v_mfma_f32_16x16x32_bf16 v[80:83], v[182:185], v[206:209], v[80:83]
	v_mfma_f32_16x16x32_bf16 v[68:71], v[164:167], v[214:217], v[68:71]
	v_mfma_f32_16x16x32_bf16 v[64:67], v[182:185], v[214:217], v[64:67]
	s_setprio 0
	s_barrier
	s_add_i32 s50, s72, s55
	v_lshl_add_u64 v[168:169], v[168:169], 0, s[16:17]
	s_mov_b32 m0, s50
	ds_read_b128 v[186:189], v176 offset:49152
	ds_read_b128 v[190:193], v176 offset:50176
	ds_read_b128 v[194:197], v176 offset:51200
	ds_read_b128 v[198:201], v176 offset:52224
	ds_read_b128 v[202:205], v176 offset:53248
	ds_read_b128 v[206:209], v176 offset:54272
	ds_read_b128 v[210:213], v176 offset:55296
	ds_read_b128 v[214:217], v176 offset:56320
	global_load_lds_dwordx4 v[168:169], off
	s_add_i32 m0, s50, 0x2000
	s_add_u32 s48, s48, 0x40080
	v_lshl_add_u64 v[168:169], v[218:219], 0, s[16:17]
	s_addc_u32 s49, s49, 0
	s_add_i32 s50, s73, s55
	global_load_lds_dwordx4 v[168:169], off
	v_lshl_add_u64 v[168:169], s[48:49], 0, v[130:131]
	s_mov_b32 m0, s50
	s_nop 0
	global_load_lds_dwordx4 v[168:169], off
	v_lshl_add_u64 v[168:169], s[48:49], 0, v[134:135]
	s_add_i32 m0, s50, 0x2000
	s_nop 0
	global_load_lds_dwordx4 v[168:169], off
	v_lshl_add_u64 v[168:169], v[220:221], 0, s[16:17]
	s_mov_b32 m0, s61
	s_nop 0
	global_load_lds_dwordx4 v[168:169], off
	v_lshl_add_u64 v[168:169], v[222:223], 0, s[16:17]
	s_mov_b32 m0, s62
	s_nop 0
	global_load_lds_dwordx4 v[168:169], off
	s_waitcnt vmcnt(8)
	s_waitcnt lgkmcnt(0)
	s_barrier
	s_setprio 1
	s_waitcnt lgkmcnt(0)
	v_mfma_f32_16x16x32_bf16 v[60:63], v[144:147], v[186:189], v[60:63]
	v_mfma_f32_16x16x32_bf16 v[56:59], v[152:155], v[186:189], v[56:59]
	v_mfma_f32_16x16x32_bf16 v[44:47], v[144:147], v[194:197], v[44:47]
	v_mfma_f32_16x16x32_bf16 v[40:43], v[152:155], v[194:197], v[40:43]
	v_mfma_f32_16x16x32_bf16 v[28:31], v[144:147], v[202:205], v[28:31]
	v_mfma_f32_16x16x32_bf16 v[24:27], v[152:155], v[202:205], v[24:27]
	v_mfma_f32_16x16x32_bf16 v[12:15], v[144:147], v[210:213], v[12:15]
	v_mfma_f32_16x16x32_bf16 v[8:11], v[152:155], v[210:213], v[8:11]
	v_mfma_f32_16x16x32_bf16 v[60:63], v[148:151], v[190:193], v[60:63]
	v_mfma_f32_16x16x32_bf16 v[56:59], v[156:159], v[190:193], v[56:59]
	v_mfma_f32_16x16x32_bf16 v[44:47], v[148:151], v[198:201], v[44:47]
	v_mfma_f32_16x16x32_bf16 v[40:43], v[156:159], v[198:201], v[40:43]
	v_mfma_f32_16x16x32_bf16 v[28:31], v[148:151], v[206:209], v[28:31]
	v_mfma_f32_16x16x32_bf16 v[24:27], v[156:159], v[206:209], v[24:27]
	v_mfma_f32_16x16x32_bf16 v[12:15], v[148:151], v[214:217], v[12:15]
	v_mfma_f32_16x16x32_bf16 v[8:11], v[156:159], v[214:217], v[8:11]
	s_setprio 0
	s_setprio 1
	v_mfma_f32_16x16x32_bf16 v[52:55], v[160:163], v[186:189], v[52:55]
	v_mfma_f32_16x16x32_bf16 v[48:51], v[178:181], v[186:189], v[48:51]
	v_mfma_f32_16x16x32_bf16 v[36:39], v[160:163], v[194:197], v[36:39]
	v_mfma_f32_16x16x32_bf16 v[32:35], v[178:181], v[194:197], v[32:35]
	v_mfma_f32_16x16x32_bf16 v[20:23], v[160:163], v[202:205], v[20:23]
	v_mfma_f32_16x16x32_bf16 v[16:19], v[178:181], v[202:205], v[16:19]
	v_mfma_f32_16x16x32_bf16 v[4:7], v[160:163], v[210:213], v[4:7]
	v_mfma_f32_16x16x32_bf16 v[0:3], v[178:181], v[210:213], v[0:3]
	v_mfma_f32_16x16x32_bf16 v[52:55], v[164:167], v[190:193], v[52:55]
	v_mfma_f32_16x16x32_bf16 v[48:51], v[182:185], v[190:193], v[48:51]
	v_mfma_f32_16x16x32_bf16 v[36:39], v[164:167], v[198:201], v[36:39]
	v_mfma_f32_16x16x32_bf16 v[32:35], v[182:185], v[198:201], v[32:35]
	v_mfma_f32_16x16x32_bf16 v[20:23], v[164:167], v[206:209], v[20:23]
	v_mfma_f32_16x16x32_bf16 v[16:19], v[182:185], v[206:209], v[16:19]
	v_mfma_f32_16x16x32_bf16 v[4:7], v[164:167], v[214:217], v[4:7]
	v_mfma_f32_16x16x32_bf16 v[0:3], v[182:185], v[214:217], v[0:3]
	s_setprio 0
	s_barrier
	s_add_i32 s71, s71, 2
	s_add_u32 s46, s46, 0x100
	s_addc_u32 s47, s47, 0
	s_add_u32 s41, s41, 0x100
	s_addc_u32 s70, s70, 0
	s_cmp_gt_u32 s71, 13
	s_cbranch_scc0 .LBB0_771
	s_and_b64 vcc, exec, s[18:19]
	s_cbranch_vccz .LBB0_774
	s_barrier

.LBB0_798:
	v_lshl_add_u32 v146, s6, 8, v171
	v_ashrrev_i32_e32 v147, 31, v146
	v_lshl_add_u64 v[144:145], v[146:147], 2, s[12:13]
	v_mov_b32_e32 v160, v230
	v_mov_b32_e32 v158, v232
	v_mov_b32_e32 v156, v234
	v_mov_b32_e32 v154, v236
	v_mov_b32_e32 v152, v238
	v_mov_b32_e32 v150, v240
	v_mov_b32_e32 v148, v242
	v_mov_b32_e32 v144, v244
	s_lshl_b32 s1, s1, 1
	s_lshr_b32 s1, 41, s1
	s_and_b32 s1, s1, 3
	s_cmp_lt_i32 s1, 2
	s_mov_b64 s[6:7], -1
	v_pk_mul_f32 v[126:127], v[126:127], v[160:161] op_sel_hi:[1,0]
	v_pk_mul_f32 v[124:125], v[124:125], v[160:161] op_sel_hi:[1,0]
	v_pk_mul_f32 v[122:123], v[122:123], v[160:161] op_sel_hi:[1,0]
	v_pk_mul_f32 v[120:121], v[120:121], v[160:161] op_sel_hi:[1,0]
	s_cbranch_scc1 .LBB0_802
	s_cmp_eq_u32 s1, 2
	v_mov_b32_e32 v167, v123
	v_mov_b32_e32 v166, v122
	v_mov_b32_e32 v169, v121
	v_mov_b32_e32 v168, v120
	v_mov_b32_e32 v165, v127
	v_mov_b32_e32 v164, v126
	v_mov_b32_e32 v163, v125
	v_mov_b32_e32 v162, v124
	s_cbranch_scc0 .LBB0_801
	v_pk_mul_f32 v[162:163], v[126:127], s[22:23] op_sel_hi:[1,0]
	v_pk_mul_f32 v[164:165], v[124:125], s[22:23] op_sel_hi:[1,0]
	v_exp_f32_e32 v162, v162
	v_exp_f32_e32 v164, v164
	v_exp_f32_e32 v163, v163
	v_exp_f32_e32 v165, v165
	v_pk_mul_f32 v[168:169], v[120:121], s[22:23] op_sel_hi:[1,0]
	v_pk_add_f32 v[166:167], v[162:163], 1.0 op_sel_hi:[1,0]
	v_pk_add_f32 v[162:163], v[164:165], 1.0 op_sel_hi:[1,0]
	v_pk_mul_f32 v[164:165], v[122:123], s[22:23] op_sel_hi:[1,0]
	v_exp_f32_e32 v168, v168
	v_exp_f32_e32 v178, v164
	v_exp_f32_e32 v179, v165
	v_exp_f32_e32 v169, v169
	v_rcp_f32_e32 v164, v166
	v_rcp_f32_e32 v165, v167
	v_pk_add_f32 v[166:167], v[178:179], 1.0 op_sel_hi:[1,0]
	v_pk_add_f32 v[168:169], v[168:169], 1.0 op_sel_hi:[1,0]
	v_rcp_f32_e32 v162, v162
	v_rcp_f32_e32 v163, v163
	v_rcp_f32_e32 v168, v168
	v_rcp_f32_e32 v169, v169
	v_rcp_f32_e32 v166, v166
	v_rcp_f32_e32 v167, v167
